# v51 + rstd loads of the phase-1 epilogue hoisted before the last MFMA clusters of the main loop
# baseline (speedup 1.0000x reference)
.LBB0_110:
	v_add_u32_e32 v0, 0x18000, v0
	s_barrier
	ds_read_b128 v[164:167], v0
	ds_read_b128 v[168:171], v0 offset:1024
	ds_read_b128 v[172:175], v0 offset:2048
	ds_read_b128 v[176:179], v0 offset:3072
	ds_read_b128 v[180:183], v227 offset:32768
	ds_read_b128 v[184:187], v227 offset:33792
	s_waitcnt lgkmcnt(0)
	ds_read_b128 v[188:191], v227 offset:34816
	ds_read_b128 v[192:195], v227 offset:35840
	ds_read_b128 v[196:199], v227 offset:36864
	ds_read_b128 v[200:203], v227 offset:37888
	ds_read_b128 v[204:207], v227 offset:38912
	ds_read_b128 v[208:211], v227 offset:39936
	s_waitcnt vmcnt(2)
	s_barrier
	s_waitcnt lgkmcnt(0)
	s_setprio 1
	v_mfma_f32_16x16x32_bf16 v[68:71], v[180:183], v[164:167], v[128:131]
	v_mfma_f32_16x16x32_bf16 v[112:115], v[184:187], v[168:171], v[68:71]
	v_mfma_f32_16x16x32_bf16 v[68:71], v[180:183], v[172:175], v[124:127]
	v_mfma_f32_16x16x32_bf16 v[108:111], v[184:187], v[176:179], v[68:71]
	s_waitcnt lgkmcnt(0)
	v_mfma_f32_16x16x32_bf16 v[68:71], v[188:191], v[164:167], v[120:123]
	v_mfma_f32_16x16x32_bf16 v[96:99], v[192:195], v[168:171], v[68:71]
	v_mfma_f32_16x16x32_bf16 v[68:71], v[188:191], v[172:175], v[116:119]
	v_mfma_f32_16x16x32_bf16 v[92:95], v[192:195], v[176:179], v[68:71]
	v_mfma_f32_16x16x32_bf16 v[68:71], v[196:199], v[164:167], v[148:151]
	v_mfma_f32_16x16x32_bf16 v[80:83], v[200:203], v[168:171], v[68:71]
	v_mfma_f32_16x16x32_bf16 v[68:71], v[196:199], v[172:175], v[152:155]
	v_mfma_f32_16x16x32_bf16 v[76:79], v[200:203], v[176:179], v[68:71]
	v_mfma_f32_16x16x32_bf16 v[68:71], v[204:207], v[164:167], v[156:159]
	v_mfma_f32_16x16x32_bf16 v[72:75], v[208:211], v[168:171], v[68:71]
	v_mfma_f32_16x16x32_bf16 v[68:71], v[204:207], v[172:175], v[160:163]
	v_mfma_f32_16x16x32_bf16 v[68:71], v[208:211], v[176:179], v[68:71]
	s_setprio 0
	s_barrier
	ds_read_b128 v[148:151], v246
	ds_read_b128 v[152:155], v246 offset:1024
	ds_read_b128 v[156:159], v246 offset:2048
	ds_read_b128 v[160:163], v246 offset:3072
	s_waitcnt vmcnt(0)
	s_barrier
	s_waitcnt lgkmcnt(0)
	s_setprio 1
	s_waitcnt lgkmcnt(0)
	v_mfma_f32_16x16x32_bf16 v[84:87], v[188:191], v[156:159], v[84:87]
	v_mfma_f32_16x16x32_bf16 v[100:103], v[180:183], v[148:151], v[100:103]
	v_mfma_f32_16x16x32_bf16 v[116:119], v[192:195], v[160:163], v[84:87]
	v_mfma_f32_16x16x32_bf16 v[84:87], v[196:199], v[148:151], v[132:135]
	v_mfma_f32_16x16x32_bf16 v[128:131], v[184:187], v[152:155], v[100:103]
	v_mfma_f32_16x16x32_bf16 v[100:103], v[180:183], v[156:159], v[104:107]
	v_mfma_f32_16x16x32_bf16 v[104:107], v[200:203], v[152:155], v[84:87]
	v_mfma_f32_16x16x32_bf16 v[84:87], v[196:199], v[156:159], v[136:139]
	v_mfma_f32_16x16x32_bf16 v[124:127], v[184:187], v[160:163], v[100:103]
	v_mfma_f32_16x16x32_bf16 v[88:91], v[188:191], v[148:151], v[88:91]
	v_mfma_f32_16x16x32_bf16 v[100:103], v[200:203], v[160:163], v[84:87]
	v_mfma_f32_16x16x32_bf16 v[84:87], v[204:207], v[148:151], v[140:143]
	v_mfma_f32_16x16x32_bf16 v[120:123], v[192:195], v[152:155], v[88:91]
	v_mfma_f32_16x16x32_bf16 v[88:91], v[208:211], v[152:155], v[84:87]
	v_mfma_f32_16x16x32_bf16 v[84:87], v[204:207], v[156:159], v[144:147]
	v_mfma_f32_16x16x32_bf16 v[84:87], v[208:211], v[160:163], v[84:87]
	s_setprio 0
	s_barrier
	ds_read_b128 v[188:191], v227 offset:49152
	ds_read_b128 v[192:195], v227 offset:50176
	ds_read_b128 v[180:183], v227 offset:51200
	ds_read_b128 v[184:187], v227 offset:52224
	ds_read_b128 v[140:143], v227 offset:53248
	ds_read_b128 v[144:147], v227 offset:54272
	ds_read_b128 v[132:135], v227 offset:55296
	ds_read_b128 v[136:139], v227 offset:56320
	s_barrier
	s_waitcnt lgkmcnt(0)
	v_ashrrev_i32_e32 v0, 2, v218
	v_and_b32_e32 v0, 0xffffffc0, v0
	v_lshrrev_b32_e32 v2, 2, v218
	v_add_u32_e32 v0, s62, v0
	v_and_or_b32 v2, v2, 12, v0
	v_ashrrev_i32_e32 v3, 31, v2
	v_lshl_add_u64 v[2:3], v[2:3], 2, s[20:21]
	global_load_dwordx4 v[202:205], v[2:3], off
	global_load_dwordx4 v[206:209], v[2:3], off offset:64
	global_load_dwordx4 v[210:213], v[2:3], off offset:128
	global_load_dwordx4 v[228:231], v[2:3], off offset:192
	global_load_dwordx4 v[232:235], v[2:3], off offset:512
	global_load_dwordx4 v[236:239], v[2:3], off offset:576
	global_load_dwordx4 v[240:243], v[2:3], off offset:640
	global_load_dwordx4 v[244:247], v[2:3], off offset:704
	s_and_b64 vcc, exec, s[6:7]
	s_cbranch_vccnz .LBB0_112
	s_setprio 1
	s_waitcnt lgkmcnt(0)
	v_mfma_f32_16x16x32_bf16 v[64:67], v[188:191], v[164:167], v[64:67]
	v_mfma_f32_16x16x32_bf16 v[60:63], v[188:191], v[172:175], v[60:63]
	v_mfma_f32_16x16x32_bf16 v[52:55], v[180:183], v[164:167], v[52:55]
	v_mfma_f32_16x16x32_bf16 v[44:47], v[180:183], v[172:175], v[44:47]
	v_mfma_f32_16x16x32_bf16 v[36:39], v[140:143], v[164:167], v[36:39]
	v_mfma_f32_16x16x32_bf16 v[28:31], v[140:143], v[172:175], v[28:31]
	v_mfma_f32_16x16x32_bf16 v[16:19], v[132:135], v[164:167], v[16:19]
	v_mfma_f32_16x16x32_bf16 v[12:15], v[132:135], v[172:175], v[12:15]
	v_mfma_f32_16x16x32_bf16 v[64:67], v[192:195], v[168:171], v[64:67]
	v_mfma_f32_16x16x32_bf16 v[60:63], v[192:195], v[176:179], v[60:63]
	v_mfma_f32_16x16x32_bf16 v[52:55], v[184:187], v[168:171], v[52:55]
	v_mfma_f32_16x16x32_bf16 v[44:47], v[184:187], v[176:179], v[44:47]
	v_mfma_f32_16x16x32_bf16 v[36:39], v[144:147], v[168:171], v[36:39]
	v_mfma_f32_16x16x32_bf16 v[28:31], v[144:147], v[176:179], v[28:31]
	v_mfma_f32_16x16x32_bf16 v[16:19], v[136:139], v[168:171], v[16:19]
	v_mfma_f32_16x16x32_bf16 v[12:15], v[136:139], v[176:179], v[12:15]
	s_setprio 0
	s_setprio 1
	v_mfma_f32_16x16x32_bf16 v[56:59], v[188:191], v[148:151], v[56:59]
	v_mfma_f32_16x16x32_bf16 v[48:51], v[188:191], v[156:159], v[48:51]
	v_mfma_f32_16x16x32_bf16 v[40:43], v[180:183], v[148:151], v[40:43]
	v_mfma_f32_16x16x32_bf16 v[32:35], v[180:183], v[156:159], v[32:35]
	v_mfma_f32_16x16x32_bf16 v[24:27], v[140:143], v[148:151], v[24:27]
	v_mfma_f32_16x16x32_bf16 v[20:23], v[140:143], v[156:159], v[20:23]
	v_mfma_f32_16x16x32_bf16 v[8:11], v[132:135], v[148:151], v[8:11]
	v_mfma_f32_16x16x32_bf16 v[2:5], v[132:135], v[156:159], v[4:7]
	v_mfma_f32_16x16x32_bf16 v[56:59], v[192:195], v[152:155], v[56:59]
	v_mfma_f32_16x16x32_bf16 v[48:51], v[192:195], v[160:163], v[48:51]
	v_mfma_f32_16x16x32_bf16 v[40:43], v[184:187], v[152:155], v[40:43]
	v_mfma_f32_16x16x32_bf16 v[32:35], v[184:187], v[160:163], v[32:35]
	v_mfma_f32_16x16x32_bf16 v[24:27], v[144:147], v[152:155], v[24:27]
	v_mfma_f32_16x16x32_bf16 v[20:23], v[144:147], v[160:163], v[20:23]
	v_mfma_f32_16x16x32_bf16 v[8:11], v[136:139], v[152:155], v[8:11]
	v_mfma_f32_16x16x32_bf16 v[4:7], v[136:139], v[160:163], v[2:5]
	s_setprio 0

.LBB0_114:
	s_or_b64 exec, exec, s[6:7]
	v_mov_b32_e32 v157, v218
	s_lshl_b32 s63, s4, 1
	v_ashrrev_i32_e32 v0, 2, v157
	v_and_b32_e32 v0, 0xffffffc0, v0
	v_lshrrev_b32_e32 v2, 2, v157
	v_add_u32_e32 v0, s62, v0
	v_and_or_b32 v2, v2, 12, v0
	v_ashrrev_i32_e32 v3, 31, v2
	s_waitcnt lgkmcnt(0)
	v_lshl_add_u64 v[140:141], v[2:3], 2, s[20:21]
	v_add_u32_e32 v140, 0x80, v2
	v_ashrrev_i32_e32 v141, 31, v140
	v_lshl_add_u64 v[140:141], v[140:141], 2, s[20:21]
	v_add_u32_e32 v140, 0x90, v2
	v_add_u32_e32 v142, 0xa0, v2
	v_add_u32_e32 v160, 0xb0, v2
	v_ashrrev_i32_e32 v141, 31, v140
	v_ashrrev_i32_e32 v143, 31, v142
	v_ashrrev_i32_e32 v161, 31, v160
	v_lshl_add_u64 v[140:141], v[140:141], 2, s[20:21]
	v_lshl_add_u64 v[142:143], v[142:143], 2, s[20:21]
	v_lshl_add_u64 v[160:161], v[160:161], 2, s[20:21]
	s_nop 0
	v_bfe_u32 v3, v157, 6, 1
	s_mov_b32 s6, 0x8200
	v_ashrrev_i32_e32 v0, 7, v157
	s_cmp_lt_i32 s5, 64
	v_lshlrev_b32_e32 v156, 5, v0
	v_lshlrev_b32_e32 v158, 9, v3
	v_mul_lo_u32 v159, v0, s6
	s_cselect_b64 s[64:65], -1, 0
	s_mov_b64 s[68:69], 0
	s_waitcnt vmcnt(0)
	v_mul_f32_e32 v163, v112, v202
	v_mul_f32_e32 v161, v114, v204
	v_mul_f32_e32 v167, v108, v202
	v_mul_f32_e32 v165, v110, v204
	v_mul_f32_e32 v128, v128, v202
	v_mul_f32_e32 v130, v130, v204
	v_mul_f32_e32 v124, v124, v202
	v_mul_f32_e32 v126, v126, v204
	v_mul_f32_e32 v171, v96, v206
	v_mul_f32_e32 v169, v98, v208
	v_mul_f32_e32 v175, v92, v206
	v_mul_f32_e32 v173, v94, v208
	v_mul_f32_e32 v120, v120, v206
	v_mul_f32_e32 v122, v122, v208
	v_mul_f32_e32 v132, v116, v206
	v_mul_f32_e32 v118, v118, v208
	v_mul_f32_e32 v180, v80, v210
	v_mul_f32_e32 v185, v76, v210
	v_mul_f32_e32 v134, v104, v210
	v_mul_f32_e32 v136, v106, v212
	v_mul_f32_e32 v138, v100, v210
	v_mul_f32_e32 v144, v102, v212
	v_mul_f32_e32 v110, v17, v245
	v_mul_f32_e32 v114, v13, v245
	v_mul_f32_e32 v102, v9, v245
	v_mul_f32_e32 v106, v5, v245
	v_or_b32_e32 v141, s63, v3
	v_mul_f32_e32 v162, v113, v203
	v_mul_f32_e32 v160, v115, v205
	v_mul_f32_e32 v166, v109, v203
	v_mul_f32_e32 v164, v111, v205
	v_mul_f32_e32 v129, v129, v203
	v_mul_f32_e32 v131, v131, v205
	v_mul_f32_e32 v125, v125, v203
	v_mul_f32_e32 v127, v127, v205
	v_mul_f32_e32 v170, v97, v207
	v_mul_f32_e32 v168, v99, v209
	v_mul_f32_e32 v174, v93, v207
	v_mul_f32_e32 v172, v95, v209
	v_mul_f32_e32 v121, v121, v207
	v_mul_f32_e32 v123, v123, v209
	v_mul_f32_e32 v117, v117, v207
	v_mul_f32_e32 v119, v119, v209
	v_mul_f32_e32 v179, v81, v211
	v_mul_f32_e32 v178, v82, v212
	v_mul_f32_e32 v177, v83, v213
	v_mul_f32_e32 v184, v77, v211
	v_mul_f32_e32 v183, v78, v212
	v_mul_f32_e32 v182, v79, v213
	v_mul_f32_e32 v135, v105, v211
	v_mul_f32_e32 v133, v107, v213
	v_mul_f32_e32 v139, v101, v211
	v_mul_f32_e32 v137, v103, v213
	v_mul_f32_e32 v189, v72, v228
	v_mul_f32_e32 v188, v73, v229
	v_mul_f32_e32 v187, v74, v230
	v_mul_f32_e32 v186, v75, v231
	v_mul_f32_e32 v193, v68, v228
	v_mul_f32_e32 v192, v69, v229
	v_mul_f32_e32 v191, v70, v230
	v_mul_f32_e32 v190, v71, v231
	v_mul_f32_e32 v146, v88, v228
	v_mul_f32_e32 v147, v89, v229
	v_mul_f32_e32 v176, v90, v230
	v_mul_f32_e32 v145, v91, v231
	v_mul_f32_e32 v181, v84, v228
	v_mul_f32_e32 v149, v85, v229
	v_mul_f32_e32 v150, v86, v230
	v_mul_f32_e32 v148, v87, v231
	v_mul_f32_e32 v64, v64, v232
	v_mul_f32_e32 v65, v65, v233
	v_mul_f32_e32 v66, v66, v234
	v_mul_f32_e32 v67, v67, v235
	v_mul_f32_e32 v68, v60, v232
	v_mul_f32_e32 v69, v61, v233
	v_mul_f32_e32 v70, v62, v234
	v_mul_f32_e32 v71, v63, v235
	v_mul_f32_e32 v56, v56, v232
	v_mul_f32_e32 v57, v57, v233
	v_mul_f32_e32 v58, v58, v234
	v_mul_f32_e32 v59, v59, v235
	v_mul_f32_e32 v60, v48, v232
	v_mul_f32_e32 v61, v49, v233
	v_mul_f32_e32 v62, v50, v234
	v_mul_f32_e32 v63, v51, v235
	v_mul_f32_e32 v77, v52, v236
	v_mul_f32_e32 v78, v53, v237
	v_mul_f32_e32 v79, v54, v238
	v_mul_f32_e32 v80, v55, v239
	v_mul_f32_e32 v81, v44, v236
	v_mul_f32_e32 v82, v45, v237
	v_mul_f32_e32 v83, v46, v238
	v_mul_f32_e32 v84, v47, v239
	v_mul_f32_e32 v54, v40, v236
	v_mul_f32_e32 v55, v41, v237
	v_mul_f32_e32 v72, v42, v238
	v_mul_f32_e32 v73, v43, v239
	v_mul_f32_e32 v74, v32, v236
	v_mul_f32_e32 v75, v33, v237
	v_mul_f32_e32 v76, v34, v238
	v_mul_f32_e32 v35, v35, v239
	v_mul_f32_e32 v93, v36, v240
	v_mul_f32_e32 v94, v37, v241
	v_mul_f32_e32 v95, v38, v242
	v_mul_f32_e32 v96, v39, v243
	v_mul_f32_e32 v97, v28, v240
	v_mul_f32_e32 v98, v29, v241
	v_mul_f32_e32 v99, v30, v242
	v_mul_f32_e32 v100, v31, v243
	v_mul_f32_e32 v85, v24, v240
	v_mul_f32_e32 v86, v25, v241
	v_mul_f32_e32 v87, v26, v242
	v_mul_f32_e32 v88, v27, v243
	v_mul_f32_e32 v89, v20, v240
	v_mul_f32_e32 v90, v21, v241
	v_mul_f32_e32 v91, v22, v242
	v_mul_f32_e32 v92, v23, v243
	v_mul_f32_e32 v109, v16, v244
	v_mul_f32_e32 v111, v18, v246
	v_mul_f32_e32 v112, v19, v247
	v_mul_f32_e32 v113, v12, v244
	v_mul_f32_e32 v115, v14, v246
	v_mul_f32_e32 v116, v15, v247
	v_mul_f32_e32 v101, v8, v244
	v_mul_f32_e32 v103, v10, v246
	v_mul_f32_e32 v104, v11, v247
	v_mul_f32_e32 v105, v4, v244
	v_mul_f32_e32 v107, v6, v246
	v_mul_f32_e32 v108, v7, v247
	v_and_b32_e32 v140, 63, v157
	v_cmp_lt_i32_e64 s[6:7], 1, v141
	s_and_saveexec_b64 s[10:11], s[6:7]
	s_xor_b64 s[10:11], exec, s[10:11]
	s_cbranch_execz .LBB0_202
	s_and_b32 s8, s4, 0x3ffffffe
	s_cmp_lg_u32 s8, 2
	s_cselect_b64 s[8:9], -1, 0
	s_cmp_lt_u32 s63, 24
	s_cselect_b64 s[66:67], -1, 0
	s_and_b64 s[66:67], s[66:67], s[8:9]
	s_mov_b64 s[8:9], -1
	s_and_b64 vcc, exec, s[66:67]
	s_cbranch_vccz .LBB0_195
	v_cmp_lt_i32_e32 vcc, 2, v141
	s_and_saveexec_b64 s[8:9], vcc
	s_xor_b64 s[66:67], exec, s[8:9]
	s_cbranch_execz .LBB0_172
	v_add_u32_e32 v151, 0, v158
	v_add_u32_e32 v143, s62, v156
	v_add_u32_e32 v142, v151, v159
	v_cmp_ne_u32_e32 vcc, 3, v141
	s_and_saveexec_b64 s[8:9], vcc
	s_xor_b64 s[68:69], exec, s[8:9]
	s_cbranch_execz .LBB0_164
	v_lshlrev_b32_e32 v0, 3, v140
	v_lshlrev_b32_e32 v36, 5, v141
	v_and_b32_e32 v34, 24, v0
	v_add_u32_e32 v0, 0xffffff00, v36
	v_mov_b32_e32 v37, v1
	v_ashrrev_i32_e32 v39, 31, v0
	v_or_b32_e32 v38, v0, v34
	v_lshl_add_u64 v[4:5], v[36:37], 2, s[18:19]
	v_lshlrev_b32_e32 v0, 2, v34
	v_lshlrev_b32_e32 v2, 7, v3
	v_readlane_b32 s8, v250, 9
	v_lshl_add_u64 v[40:41], v[4:5], 0, v[0:1]
	v_lshrrev_b32_e32 v152, 2, v140
	v_add3_u32 v194, s8, v0, v2
	v_ashrrev_i32_e32 v0, 12, v143
	v_cmp_gt_u32_e32 vcc, s85, v143
	v_cmp_lt_u32_e64 s[8:9], 55, v140
	v_and_b32_e32 v0, -2, v0
	v_add_u32_e32 v196, 0x400, v219
	v_add_u32_e32 v197, 0x800, v219
	v_add_u32_e32 v198, 0xc00, v219
	v_add_u32_e32 v199, 0x4000, v219
	v_add_u32_e32 v200, 0x4400, v219
	v_add_u32_e32 v201, 0x4800, v219
	v_add_u32_e32 v202, 0x4c00, v219
	v_add_u32_e32 v209, 0x8000, v219
	v_add_u32_e32 v203, 0x8400, v219
	v_add_u32_e32 v204, 0x8800, v219
	v_add_u32_e32 v205, 0x8c00, v219
	v_add_u32_e32 v210, 0xc000, v219
	v_add_u32_e32 v206, 0xc400, v219
	v_add_u32_e32 v207, 0xc800, v219
	v_add_u32_e32 v208, 0xcc00, v219
	v_add_u32_e32 v211, 0x9000, v219
	v_add_u32_e32 v212, 0xd000, v219
	v_or_b32_e32 v153, 32, v34
	v_or_b32_e32 v154, 64, v34
	v_or_b32_e32 v155, 0x60, v34
	v_add_u32_e32 v213, 0xffff8200, v194
	s_and_b64 s[70:71], vcc, s[8:9]
	v_add_u32_e32 v195, -14, v152
	v_add_u32_e32 v226, 0xffffe002, v0
	s_mov_b32 s74, 0
	s_mov_b64 s[72:73], -1
	s_barrier
	ds_write2_b32 v219, v163, v167 offset1:16
	ds_write2_b32 v196, v162, v166 offset0:4 offset1:20
	ds_write2_b32 v197, v161, v165 offset0:8 offset1:24
	ds_write2_b32 v198, v160, v164 offset0:12 offset1:28
	ds_write2_b32 v199, v171, v175 offset0:64 offset1:80
	ds_write2_b32 v200, v170, v174 offset0:68 offset1:84
	ds_write2_b32 v201, v169, v173 offset0:72 offset1:88
	ds_write2_b32 v202, v168, v172 offset0:76 offset1:92
	ds_write2_b32 v209, v180, v185 offset0:128 offset1:144
	ds_write2_b32 v203, v179, v184 offset0:132 offset1:148
	ds_write2_b32 v204, v178, v183 offset0:136 offset1:152
	ds_write2_b32 v205, v177, v182 offset0:140 offset1:156
	ds_write2_b32 v210, v189, v193 offset0:192 offset1:208
	ds_write2_b32 v206, v188, v192 offset0:196 offset1:212
	ds_write2_b32 v207, v187, v191 offset0:200 offset1:216
	ds_write2_b32 v208, v186, v190 offset0:204 offset1:220
	ds_write2_b32 v219, v128, v124 offset0:128 offset1:144
	ds_write2_b32 v196, v129, v125 offset0:132 offset1:148
	ds_write2_b32 v197, v130, v126 offset0:136 offset1:152
	ds_write2_b32 v198, v131, v127 offset0:140 offset1:156
	ds_write2_b32 v199, v120, v132 offset0:192 offset1:208
	ds_write2_b32 v200, v121, v117 offset0:196 offset1:212
	ds_write2_b32 v201, v122, v118 offset0:200 offset1:216
	ds_write2_b32 v202, v123, v119 offset0:204 offset1:220
	ds_write2_b32 v203, v134, v138 offset1:16
	ds_write2_b32 v204, v135, v139 offset0:4 offset1:20
	ds_write2_b32 v205, v136, v144 offset0:8 offset1:24
	ds_write2_b32 v211, v133, v137 offset0:12 offset1:28
	ds_write2_b32 v206, v146, v181 offset0:64 offset1:80
	ds_write2_b32 v207, v147, v149 offset0:68 offset1:84
	ds_write2_b32 v208, v176, v150 offset0:72 offset1:88
	ds_write2_b32 v212, v145, v148 offset0:76 offset1:92
	s_waitcnt lgkmcnt(0)
	s_barrier
	s_branch .LBB0_120
